# GEMM2 / GEMM4 epilogues: nt policy on the once-read residual loads (x f32, h1 bf16)
# speedup vs baseline: 1.0052x; 1.0021x over previous
;     DI void operator()(const f32x4 (&acc)[2][2][4][2], const Unit& u, int wr, int wc, int fr, int fq) const {
;         const int row0 = u.pm * BM + wr * 64 + fr, col0 = u.pn * BM + wc * 32 + 8 * fq;
;         f32x4 nx32[2][2]; u32x4 nx16[2];
;         if (base32) {
; #pragma unroll
;             for (int bj = 0; bj < 2; ++bj)
; #pragma unroll
;                 for (int n = 0; n < 2; ++n) nx32[bj][n] = *(const f32x4*)(base32 + (size_t)row0 * 4096 + col0 + bj * HALF + 4 * n);
.LBB0_441:
	v_readlane_b32 s76, v253, 3
	v_lshlrev_b64 v[134:135], 14, v[184:185]
	v_readlane_b32 s77, v253, 4
	s_waitcnt vmcnt(0) lgkmcnt(0)
	v_mov_b32_e32 v146, 0
	v_mov_b32_e32 v147, 0
	v_lshl_add_u64 v[134:135], s[76:77], 0, v[134:135]
	v_lshl_add_u64 v[138:139], v[4:5], 2, v[134:135]
	global_load_dwordx4 v[150:153], v[138:139], off offset:16 nt
	global_load_dwordx4 v[154:157], v[138:139], off nt
	global_load_dwordx4 v[134:137], v[138:139], off offset:528 nt
	s_nop 0
	global_load_dwordx4 v[138:141], v[138:139], off offset:512 nt
	v_mov_b32_e32 v148, 0
	v_mov_b32_e32 v149, 0
	v_mov_b32_e32 v142, 0
	v_mov_b32_e32 v143, 0
	v_mov_b32_e32 v144, 0
	v_mov_b32_e32 v145, 0
	v_readlane_b32 s78, v253, 5
	v_readlane_b32 s79, v253, 6
	v_readlane_b32 s80, v253, 7
	v_readlane_b32 s81, v253, 8
	v_readlane_b32 s82, v253, 9
	v_readlane_b32 s83, v253, 10
	v_readlane_b32 s84, v253, 11
	v_readlane_b32 s85, v253, 12
	v_readlane_b32 s86, v253, 13
	v_readlane_b32 s87, v253, 14
	v_readlane_b32 s88, v253, 15
	v_readlane_b32 s89, v253, 16
	v_readlane_b32 s90, v253, 17
	v_readlane_b32 s91, v253, 18
	s_andn2_b64 vcc, exec, s[18:19]
	s_cbranch_vccnz .LBB0_445

; DI float bflo(unsigned w) { return __uint_as_float(w << 16); }
; DI float bfhi(unsigned w) { return __uint_as_float(w & 0xffff0000u); }
; DI unsigned cvt_pk_bf16(float lo, float hi) { f32x2 v = {lo, hi}; bf16v2 b = __builtin_convertvector(v, bf16v2); return __builtin_bit_cast(unsigned, b); }
;     DI void operator()(const f32x4 (&acc)[2][2][4][2], const Unit& u, int wr, int wc, int fr, int fq) const {
;     ...
;         for (int g = 0; g < 8; ++g) { const int ai = g >> 2, m = g & 3; const int row = row0 + ai * HALF + m * 16; const size_t off = (size_t)row * 4096 + col0;
;             f32x4 cur[2][2];
;             if (base32) {
; #pragma unroll
;                 for (int bj = 0; bj < 2; ++bj)
; #pragma unroll
;                     for (int n = 0; n < 2; ++n) cur[bj][n] = nx32[bj][n];
;             } else {
; #pragma unroll
;                 for (int bj = 0; bj < 2; ++bj) { const u32x4 w = nx16[bj]; cur[bj][0] = (f32x4){bflo(w.x), bfhi(w.x), bflo(w.y), bfhi(w.y)}; cur[bj][1] = (f32x4){bflo(w.z), bfhi(w.z), bflo(w.w), bfhi(w.w)}; }
;             }
;             if (g + 1 < 8) { const size_t offn = (size_t)(row0 + ((g + 1) >> 2) * HALF + ((g + 1) & 3) * 16) * 4096 + col0;
;                 if (base32) {
; #pragma unroll
;                     for (int bj = 0; bj < 2; ++bj)
; #pragma unroll
;                         for (int n = 0; n < 2; ++n) nx32[bj][n] = *(const f32x4*)(base32 + offn + bj * HALF + 4 * n);
;                 } else {
; #pragma unroll
;                     for (int bj = 0; bj < 2; ++bj) nx16[bj] = *(const u32x4*)(base16 + offn + bj * HALF);
;                 } }
;             const float s = ssq_epi ? __builtin_amdgcn_rsqf(ssq_epi[row] * (1.0f / 8192.0f) + 1e-6f) : 1.0f;
;             float ss = 0.f;
; #pragma unroll
;             for (int bj = 0; bj < 2; ++bj) { const f32x4 v0 = cur[bj][0] + acc[ai][bj][m][0] * s, v1 = cur[bj][1] + acc[ai][bj][m][1] * s;
;                 ss += ((v0[0] * v0[0] + v0[1] * v0[1]) + (v0[2] * v0[2] + v0[3] * v0[3])) + ((v1[0] * v1[0] + v1[1] * v1[1]) + (v1[2] * v1[2] + v1[3] * v1[3]));
;                 u32x4 w; w.x = cvt_pk_bf16(v0[0], v0[1]); w.y = cvt_pk_bf16(v0[2], v0[3]); w.z = cvt_pk_bf16(v1[0], v1[1]); w.w = cvt_pk_bf16(v1[2], v1[3]);
;                 *(u32x4*)(O + off + bj * HALF) = w; }
;             ss = fq_sum(ss);
;             if (fq == 0) unsafeAtomicAdd(ssq_out + row, ss);
.LBB0_445:
	v_or_b32_e32 v190, 16, v184
	v_readlane_b32 s76, v253, 3
	v_ashrrev_i32_e32 v191, 31, v190
	v_readlane_b32 s77, v253, 4
	s_waitcnt vmcnt(0) lgkmcnt(0)
	v_lshlrev_b64 v[142:143], 14, v[190:191]
	v_pk_add_f32 v[132:133], v[132:133], v[156:157]
	v_lshl_add_u64 v[186:187], v[4:5], 2, s[76:77]
	v_lshl_add_u64 v[146:147], v[186:187], 0, v[142:143]
	global_load_dwordx4 v[158:161], v[146:147], off offset:16 nt
	global_load_dwordx4 v[162:165], v[146:147], off nt
	global_load_dwordx4 v[142:145], v[146:147], off offset:528 nt
	s_nop 0
	global_load_dwordx4 v[146:149], v[146:147], off offset:512 nt
	v_pk_add_f32 v[130:131], v[130:131], v[154:155]
	v_pk_add_f32 v[152:153], v[128:129], v[152:153]
	v_pk_add_f32 v[128:129], v[126:127], v[150:151]
	v_mul_f32_e32 v3, v131, v131
	v_mul_f32_e32 v126, v133, v133
	v_fmac_f32_e32 v3, v130, v130
	v_fmac_f32_e32 v126, v132, v132
	v_add_f32_e32 v3, v3, v126
	v_mul_f32_e32 v126, v129, v129
	v_mul_f32_e32 v127, v153, v153
	v_fmac_f32_e32 v126, v128, v128
	v_fmac_f32_e32 v127, v152, v152
	v_add_f32_e32 v126, v126, v127
	v_add_f32_e32 v3, v126, v3
	v_cvt_pk_bf16_f32 v126, v130, v131
	v_lshl_add_u64 v[130:131], s[42:43], 0, v[188:189]
	v_cvt_pk_bf16_f32 v127, v132, v133
	v_cvt_pk_bf16_f32 v128, v128, v129
	v_cvt_pk_bf16_f32 v129, v152, v153
	v_lshl_add_u64 v[130:131], v[4:5], 1, v[130:131]
	v_pk_add_f32 v[124:125], v[124:125], v[140:141]
	v_pk_add_f32 v[122:123], v[122:123], v[138:139]
	global_store_dwordx4 v[130:131], v[126:129], off
	v_readlane_b32 s78, v253, 5
	v_readlane_b32 s79, v253, 6
	v_pk_add_f32 v[126:127], v[120:121], v[136:137]
	v_pk_add_f32 v[120:121], v[118:119], v[134:135]
	v_mul_f32_e32 v118, v123, v123
	v_mul_f32_e32 v119, v125, v125
	v_fmac_f32_e32 v118, v122, v122
	v_fmac_f32_e32 v119, v124, v124
	v_add_f32_e32 v118, v118, v119
	v_mul_f32_e32 v119, v121, v121
	v_mul_f32_e32 v128, v127, v127
	v_fmac_f32_e32 v119, v120, v120
	v_fmac_f32_e32 v128, v126, v126
	v_add_f32_e32 v119, v119, v128
	v_add_f32_e32 v118, v119, v118
	v_add_f32_e32 v3, v118, v3
	v_cvt_pk_bf16_f32 v118, v122, v123
	v_cvt_pk_bf16_f32 v119, v124, v125
	v_cvt_pk_bf16_f32 v120, v120, v121
	v_cvt_pk_bf16_f32 v121, v126, v127
	global_store_dwordx4 v[130:131], v[118:121], off offset:256
	v_lshl_add_u64 v[134:135], v[184:185], 2, s[12:13]
	v_readlane_b32 s80, v253, 7
	v_mov_b32_e32 v118, v3
	s_nop 1
	v_permlane16_swap_b32_e32 v3, v118
	v_add_f32_e32 v3, v3, v118
	v_mov_b32_e32 v118, v3
	s_nop 1
	v_permlane32_swap_b32_e32 v3, v118
	v_readlane_b32 s81, v253, 8
	v_readlane_b32 s82, v253, 9
	v_readlane_b32 s83, v253, 10
	v_readlane_b32 s84, v253, 11
	v_readlane_b32 s85, v253, 12
	v_readlane_b32 s86, v253, 13
	v_readlane_b32 s87, v253, 14
	v_readlane_b32 s88, v253, 15
	v_readlane_b32 s89, v253, 16
	v_readlane_b32 s90, v253, 17
	v_readlane_b32 s91, v253, 18
	s_and_saveexec_b64 s[4:5], s[0:1]
	s_cbranch_execz .LBB0_447
	v_add_f32_e32 v3, v3, v118
	global_atomic_add_f32 v[134:135], v3, off
.LBB0_447:
	s_or_b64 exec, exec, s[4:5]
	v_or_b32_e32 v136, 32, v184
	v_ashrrev_i32_e32 v137, 31, v136
	v_lshlrev_b64 v[118:119], 14, v[136:137]
	v_lshl_add_u64 v[122:123], v[186:187], 0, v[118:119]
	global_load_dwordx4 v[126:129], v[122:123], off offset:16 nt
	global_load_dwordx4 v[130:133], v[122:123], off nt
	global_load_dwordx4 v[118:121], v[122:123], off offset:528 nt
	s_nop 0
	global_load_dwordx4 v[122:125], v[122:123], off offset:512 nt
	s_waitcnt vmcnt(8)
	v_pk_add_f32 v[116:117], v[116:117], v[164:165]
	v_pk_add_f32 v[114:115], v[114:115], v[162:163]
	v_pk_add_f32 v[140:141], v[112:113], v[160:161]
	v_pk_add_f32 v[112:113], v[110:111], v[158:159]
	v_mul_f32_e32 v3, v115, v115
	v_mul_f32_e32 v110, v117, v117
	v_fmac_f32_e32 v3, v114, v114
	v_fmac_f32_e32 v110, v116, v116
	v_add_f32_e32 v3, v3, v110
	v_mul_f32_e32 v110, v113, v113
	v_mul_f32_e32 v111, v141, v141
	v_fmac_f32_e32 v110, v112, v112
	v_fmac_f32_e32 v111, v140, v140
	v_lshlrev_b64 v[138:139], 13, v[190:191]
	v_add_f32_e32 v110, v110, v111
	v_add_f32_e32 v3, v110, v3
	v_cvt_pk_bf16_f32 v110, v114, v115
	v_lshl_add_u64 v[114:115], s[42:43], 0, v[138:139]
	v_cvt_pk_bf16_f32 v111, v116, v117
	v_cvt_pk_bf16_f32 v112, v112, v113
	v_cvt_pk_bf16_f32 v113, v140, v141
	v_lshl_add_u64 v[114:115], v[4:5], 1, v[114:115]
	s_waitcnt vmcnt(6)
	v_pk_add_f32 v[108:109], v[108:109], v[148:149]
	v_pk_add_f32 v[106:107], v[106:107], v[146:147]
	global_store_dwordx4 v[114:115], v[110:113], off
	s_nop 1
	v_pk_add_f32 v[110:111], v[104:105], v[144:145]
	v_pk_add_f32 v[104:105], v[102:103], v[142:143]
	v_mul_f32_e32 v102, v107, v107
	v_mul_f32_e32 v103, v109, v109
	v_fmac_f32_e32 v102, v106, v106
	v_fmac_f32_e32 v103, v108, v108
	v_add_f32_e32 v102, v102, v103
	v_mul_f32_e32 v103, v105, v105
	v_mul_f32_e32 v112, v111, v111
	v_fmac_f32_e32 v103, v104, v104
	v_fmac_f32_e32 v112, v110, v110
	v_add_f32_e32 v103, v103, v112
	v_add_f32_e32 v102, v103, v102
	v_add_f32_e32 v3, v102, v3
	v_cvt_pk_bf16_f32 v102, v106, v107
	v_cvt_pk_bf16_f32 v103, v108, v109
	v_cvt_pk_bf16_f32 v104, v104, v105
	v_cvt_pk_bf16_f32 v105, v110, v111
	global_store_dwordx4 v[114:115], v[102:105], off offset:256
	s_nop 1
	v_mov_b32_e32 v102, v3
	s_nop 1
	v_permlane16_swap_b32_e32 v3, v102
	v_add_f32_e32 v3, v3, v102
	v_mov_b32_e32 v102, v3
	s_nop 1
	v_permlane32_swap_b32_e32 v3, v102
	s_and_saveexec_b64 s[4:5], s[0:1]
	s_cbranch_execz .LBB0_449
	v_add_f32_e32 v3, v3, v102
	global_atomic_add_f32 v[134:135], v3, off offset:64
; DI float bflo(unsigned w) { return __uint_as_float(w << 16); }
; DI float bfhi(unsigned w) { return __uint_as_float(w & 0xffff0000u); }
; DI unsigned cvt_pk_bf16(float lo, float hi) { f32x2 v = {lo, hi}; bf16v2 b = __builtin_convertvector(v, bf16v2); return __builtin_bit_cast(unsigned, b); }
;     DI void operator()(const f32x4 (&acc)[2][2][4][2], const Unit& u, int wr, int wc, int fr, int fq) const {
;     ...
;         for (int g = 0; g < 8; ++g) { const int ai = g >> 2, m = g & 3; const int row = row0 + ai * HALF + m * 16; const size_t off = (size_t)row * 4096 + col0;
;             f32x4 cur[2][2];
;             if (base32) {
; #pragma unroll
;                 for (int bj = 0; bj < 2; ++bj)
; #pragma unroll
;                     for (int n = 0; n < 2; ++n) cur[bj][n] = nx32[bj][n];
;             } else {
; #pragma unroll
;                 for (int bj = 0; bj < 2; ++bj) { const u32x4 w = nx16[bj]; cur[bj][0] = (f32x4){bflo(w.x), bfhi(w.x), bflo(w.y), bfhi(w.y)}; cur[bj][1] = (f32x4){bflo(w.z), bfhi(w.z), bflo(w.w), bfhi(w.w)}; }
;             }
;             if (g + 1 < 8) { const size_t offn = (size_t)(row0 + ((g + 1) >> 2) * HALF + ((g + 1) & 3) * 16) * 4096 + col0;
;                 if (base32) {
; #pragma unroll
;                     for (int bj = 0; bj < 2; ++bj)
; #pragma unroll
;                         for (int n = 0; n < 2; ++n) nx32[bj][n] = *(const f32x4*)(base32 + offn + bj * HALF + 4 * n);
;                 } else {
; #pragma unroll
;                     for (int bj = 0; bj < 2; ++bj) nx16[bj] = *(const u32x4*)(base16 + offn + bj * HALF);
;                 } }
;             const float s = ssq_epi ? __builtin_amdgcn_rsqf(ssq_epi[row] * (1.0f / 8192.0f) + 1e-6f) : 1.0f;
;             float ss = 0.f;
; #pragma unroll
;             for (int bj = 0; bj < 2; ++bj) { const f32x4 v0 = cur[bj][0] + acc[ai][bj][m][0] * s, v1 = cur[bj][1] + acc[ai][bj][m][1] * s;
;                 ss += ((v0[0] * v0[0] + v0[1] * v0[1]) + (v0[2] * v0[2] + v0[3] * v0[3])) + ((v1[0] * v1[0] + v1[1] * v1[1]) + (v1[2] * v1[2] + v1[3] * v1[3]));
;                 u32x4 w; w.x = cvt_pk_bf16(v0[0], v0[1]); w.y = cvt_pk_bf16(v0[2], v0[3]); w.z = cvt_pk_bf16(v1[0], v1[1]); w.w = cvt_pk_bf16(v1[2], v1[3]);
;                 *(u32x4*)(O + off + bj * HALF) = w; }
;             ss = fq_sum(ss);
;             if (fq == 0) unsafeAtomicAdd(ssq_out + row, ss);
.LBB0_449:
	s_or_b64 exec, exec, s[4:5]
	v_or_b32_e32 v138, 48, v184
	v_ashrrev_i32_e32 v139, 31, v138
	v_lshlrev_b64 v[102:103], 14, v[138:139]
	v_lshl_add_u64 v[106:107], v[186:187], 0, v[102:103]
	global_load_dwordx4 v[110:113], v[106:107], off offset:16 nt
	global_load_dwordx4 v[114:117], v[106:107], off nt
	global_load_dwordx4 v[102:105], v[106:107], off offset:528 nt
	s_nop 0
	global_load_dwordx4 v[106:109], v[106:107], off offset:512 nt
	s_waitcnt vmcnt(8)
	v_pk_add_f32 v[100:101], v[100:101], v[132:133]
	v_pk_add_f32 v[98:99], v[98:99], v[130:131]
	v_pk_add_f32 v[128:129], v[96:97], v[128:129]
	v_pk_add_f32 v[96:97], v[94:95], v[126:127]
	v_mul_f32_e32 v3, v99, v99
	v_mul_f32_e32 v94, v101, v101
	v_fmac_f32_e32 v3, v98, v98
	v_fmac_f32_e32 v94, v100, v100
	v_add_f32_e32 v3, v3, v94
	v_mul_f32_e32 v94, v97, v97
	v_mul_f32_e32 v95, v129, v129
	v_fmac_f32_e32 v94, v96, v96
	v_fmac_f32_e32 v95, v128, v128
	v_lshlrev_b64 v[136:137], 13, v[136:137]
	v_add_f32_e32 v94, v94, v95
	v_add_f32_e32 v3, v94, v3
	v_cvt_pk_bf16_f32 v94, v98, v99
	v_lshl_add_u64 v[98:99], s[42:43], 0, v[136:137]
	v_cvt_pk_bf16_f32 v95, v100, v101
	v_cvt_pk_bf16_f32 v96, v96, v97
	v_cvt_pk_bf16_f32 v97, v128, v129
	v_lshl_add_u64 v[98:99], v[4:5], 1, v[98:99]
	s_waitcnt vmcnt(6)
	v_pk_add_f32 v[92:93], v[92:93], v[124:125]
	v_pk_add_f32 v[90:91], v[90:91], v[122:123]
	global_store_dwordx4 v[98:99], v[94:97], off
	s_nop 1
	v_pk_add_f32 v[94:95], v[88:89], v[120:121]
	v_pk_add_f32 v[88:89], v[86:87], v[118:119]
	v_mul_f32_e32 v86, v91, v91
	v_mul_f32_e32 v87, v93, v93
	v_fmac_f32_e32 v86, v90, v90
	v_fmac_f32_e32 v87, v92, v92
	v_add_f32_e32 v86, v86, v87
	v_mul_f32_e32 v87, v89, v89
	v_mul_f32_e32 v96, v95, v95
	v_fmac_f32_e32 v87, v88, v88
	v_fmac_f32_e32 v96, v94, v94
	v_add_f32_e32 v87, v87, v96
	v_add_f32_e32 v86, v87, v86
	v_add_f32_e32 v3, v86, v3
	v_cvt_pk_bf16_f32 v86, v90, v91
	v_cvt_pk_bf16_f32 v87, v92, v93
	v_cvt_pk_bf16_f32 v88, v88, v89
	v_cvt_pk_bf16_f32 v89, v94, v95
	global_store_dwordx4 v[98:99], v[86:89], off offset:256
	s_nop 1
	v_mov_b32_e32 v86, v3
	s_nop 1
	v_permlane16_swap_b32_e32 v3, v86
	v_add_f32_e32 v3, v3, v86
	v_mov_b32_e32 v86, v3
	s_nop 1
	v_permlane32_swap_b32_e32 v3, v86
	s_and_saveexec_b64 s[4:5], s[0:1]
	s_cbranch_execz .LBB0_451
	v_add_f32_e32 v3, v3, v86
	global_atomic_add_f32 v[134:135], v3, off offset:128
.LBB0_451:
	s_or_b64 exec, exec, s[4:5]
	v_add_u32_e32 v118, 0x80, v184
	v_ashrrev_i32_e32 v119, 31, v118
	v_lshlrev_b64 v[86:87], 14, v[118:119]
	v_lshl_add_u64 v[90:91], v[186:187], 0, v[86:87]
	global_load_dwordx4 v[94:97], v[90:91], off offset:16 nt
	global_load_dwordx4 v[98:101], v[90:91], off nt
	global_load_dwordx4 v[86:89], v[90:91], off offset:528 nt
	s_nop 0
	global_load_dwordx4 v[90:93], v[90:91], off offset:512 nt
	s_waitcnt vmcnt(8)
	v_pk_add_f32 v[84:85], v[84:85], v[116:117]
	v_pk_add_f32 v[82:83], v[82:83], v[114:115]
	v_pk_add_f32 v[112:113], v[80:81], v[112:113]
	v_pk_add_f32 v[80:81], v[78:79], v[110:111]
	v_mul_f32_e32 v3, v83, v83
	v_mul_f32_e32 v78, v85, v85
	v_fmac_f32_e32 v3, v82, v82
	v_fmac_f32_e32 v78, v84, v84
	v_add_f32_e32 v3, v3, v78
	v_mul_f32_e32 v78, v81, v81
	v_mul_f32_e32 v79, v113, v113
	v_fmac_f32_e32 v78, v80, v80
	v_fmac_f32_e32 v79, v112, v112
	v_lshlrev_b64 v[120:121], 13, v[138:139]
	v_add_f32_e32 v78, v78, v79
	v_add_f32_e32 v3, v78, v3
	v_cvt_pk_bf16_f32 v78, v82, v83
	v_lshl_add_u64 v[82:83], s[42:43], 0, v[120:121]
	v_cvt_pk_bf16_f32 v79, v84, v85
	v_cvt_pk_bf16_f32 v80, v80, v81
	v_cvt_pk_bf16_f32 v81, v112, v113
	v_lshl_add_u64 v[82:83], v[4:5], 1, v[82:83]
	s_waitcnt vmcnt(6)
	v_pk_add_f32 v[76:77], v[76:77], v[108:109]
	v_pk_add_f32 v[74:75], v[74:75], v[106:107]
	global_store_dwordx4 v[82:83], v[78:81], off
	s_nop 1
	v_pk_add_f32 v[78:79], v[72:73], v[104:105]
	v_pk_add_f32 v[72:73], v[70:71], v[102:103]
	v_mul_f32_e32 v70, v75, v75
	v_mul_f32_e32 v71, v77, v77
	v_fmac_f32_e32 v70, v74, v74
	v_fmac_f32_e32 v71, v76, v76
	v_add_f32_e32 v70, v70, v71
	v_mul_f32_e32 v71, v73, v73
	v_mul_f32_e32 v80, v79, v79
	v_fmac_f32_e32 v71, v72, v72
	v_fmac_f32_e32 v80, v78, v78
	v_add_f32_e32 v71, v71, v80
	v_add_f32_e32 v70, v71, v70
	v_add_f32_e32 v3, v70, v3
	v_cvt_pk_bf16_f32 v70, v74, v75
	v_cvt_pk_bf16_f32 v71, v76, v77
	v_cvt_pk_bf16_f32 v72, v72, v73
	v_cvt_pk_bf16_f32 v73, v78, v79
	global_store_dwordx4 v[82:83], v[70:73], off offset:256
	s_nop 1
	v_mov_b32_e32 v70, v3
	s_nop 1
	v_permlane16_swap_b32_e32 v3, v70
	v_add_f32_e32 v3, v3, v70
	v_mov_b32_e32 v70, v3
	s_nop 1
	v_permlane32_swap_b32_e32 v3, v70
	s_and_saveexec_b64 s[4:5], s[0:1]
	s_cbranch_execz .LBB0_453
	v_add_f32_e32 v3, v3, v70
	global_atomic_add_f32 v[134:135], v3, off offset:192
; DI float bflo(unsigned w) { return __uint_as_float(w << 16); }
; DI float bfhi(unsigned w) { return __uint_as_float(w & 0xffff0000u); }
; DI unsigned cvt_pk_bf16(float lo, float hi) { f32x2 v = {lo, hi}; bf16v2 b = __builtin_convertvector(v, bf16v2); return __builtin_bit_cast(unsigned, b); }
;     DI void operator()(const f32x4 (&acc)[2][2][4][2], const Unit& u, int wr, int wc, int fr, int fq) const {
;     ...
;         for (int g = 0; g < 8; ++g) { const int ai = g >> 2, m = g & 3; const int row = row0 + ai * HALF + m * 16; const size_t off = (size_t)row * 4096 + col0;
;             f32x4 cur[2][2];
;             if (base32) {
; #pragma unroll
;                 for (int bj = 0; bj < 2; ++bj)
; #pragma unroll
;                     for (int n = 0; n < 2; ++n) cur[bj][n] = nx32[bj][n];
;             } else {
; #pragma unroll
;                 for (int bj = 0; bj < 2; ++bj) { const u32x4 w = nx16[bj]; cur[bj][0] = (f32x4){bflo(w.x), bfhi(w.x), bflo(w.y), bfhi(w.y)}; cur[bj][1] = (f32x4){bflo(w.z), bfhi(w.z), bflo(w.w), bfhi(w.w)}; }
;             }
;             if (g + 1 < 8) { const size_t offn = (size_t)(row0 + ((g + 1) >> 2) * HALF + ((g + 1) & 3) * 16) * 4096 + col0;
;                 if (base32) {
; #pragma unroll
;                     for (int bj = 0; bj < 2; ++bj)
; #pragma unroll
;                         for (int n = 0; n < 2; ++n) nx32[bj][n] = *(const f32x4*)(base32 + offn + bj * HALF + 4 * n);
;                 } else {
; #pragma unroll
;                     for (int bj = 0; bj < 2; ++bj) nx16[bj] = *(const u32x4*)(base16 + offn + bj * HALF);
;                 } }
;             const float s = ssq_epi ? __builtin_amdgcn_rsqf(ssq_epi[row] * (1.0f / 8192.0f) + 1e-6f) : 1.0f;
;             float ss = 0.f;
; #pragma unroll
;             for (int bj = 0; bj < 2; ++bj) { const f32x4 v0 = cur[bj][0] + acc[ai][bj][m][0] * s, v1 = cur[bj][1] + acc[ai][bj][m][1] * s;
;                 ss += ((v0[0] * v0[0] + v0[1] * v0[1]) + (v0[2] * v0[2] + v0[3] * v0[3])) + ((v1[0] * v1[0] + v1[1] * v1[1]) + (v1[2] * v1[2] + v1[3] * v1[3]));
;                 u32x4 w; w.x = cvt_pk_bf16(v0[0], v0[1]); w.y = cvt_pk_bf16(v0[2], v0[3]); w.z = cvt_pk_bf16(v1[0], v1[1]); w.w = cvt_pk_bf16(v1[2], v1[3]);
;                 *(u32x4*)(O + off + bj * HALF) = w; }
;             ss = fq_sum(ss);
;             if (fq == 0) unsafeAtomicAdd(ssq_out + row, ss);
.LBB0_453:
	s_or_b64 exec, exec, s[4:5]
	v_or_b32_e32 v102, 16, v118
	v_ashrrev_i32_e32 v103, 31, v102
	v_lshlrev_b64 v[70:71], 14, v[102:103]
	v_lshl_add_u64 v[74:75], v[186:187], 0, v[70:71]
	global_load_dwordx4 v[78:81], v[74:75], off offset:16 nt
	global_load_dwordx4 v[82:85], v[74:75], off nt
	global_load_dwordx4 v[70:73], v[74:75], off offset:528 nt
	s_nop 0
	global_load_dwordx4 v[74:77], v[74:75], off offset:512 nt
	s_waitcnt vmcnt(8)
	v_pk_add_f32 v[68:69], v[68:69], v[100:101]
	v_pk_add_f32 v[66:67], v[66:67], v[98:99]
	v_pk_add_f32 v[96:97], v[64:65], v[96:97]
	v_pk_add_f32 v[64:65], v[62:63], v[94:95]
	v_mul_f32_e32 v3, v67, v67
	v_mul_f32_e32 v62, v69, v69
	v_fmac_f32_e32 v3, v66, v66
	v_fmac_f32_e32 v62, v68, v68
	v_add_f32_e32 v3, v3, v62
	v_mul_f32_e32 v62, v65, v65
	v_mul_f32_e32 v63, v97, v97
	v_fmac_f32_e32 v62, v64, v64
	v_fmac_f32_e32 v63, v96, v96
	v_lshlrev_b64 v[104:105], 13, v[118:119]
	v_add_f32_e32 v62, v62, v63
	v_add_f32_e32 v3, v62, v3
	v_cvt_pk_bf16_f32 v62, v66, v67
	v_lshl_add_u64 v[66:67], s[42:43], 0, v[104:105]
	v_cvt_pk_bf16_f32 v63, v68, v69
	v_cvt_pk_bf16_f32 v64, v64, v65
	v_cvt_pk_bf16_f32 v65, v96, v97
	v_lshl_add_u64 v[66:67], v[4:5], 1, v[66:67]
	s_waitcnt vmcnt(6)
	v_pk_add_f32 v[60:61], v[60:61], v[92:93]
	v_pk_add_f32 v[58:59], v[58:59], v[90:91]
	global_store_dwordx4 v[66:67], v[62:65], off
	s_nop 1
	v_pk_add_f32 v[62:63], v[56:57], v[88:89]
	v_pk_add_f32 v[56:57], v[54:55], v[86:87]
	v_mul_f32_e32 v54, v59, v59
	v_mul_f32_e32 v55, v61, v61
	v_fmac_f32_e32 v54, v58, v58
	v_fmac_f32_e32 v55, v60, v60
	v_add_f32_e32 v54, v54, v55
	v_mul_f32_e32 v55, v57, v57
	v_mul_f32_e32 v64, v63, v63
	v_fmac_f32_e32 v55, v56, v56
	v_fmac_f32_e32 v64, v62, v62
	v_add_f32_e32 v55, v55, v64
	v_add_f32_e32 v54, v55, v54
	v_add_f32_e32 v3, v54, v3
	v_cvt_pk_bf16_f32 v54, v58, v59
	v_cvt_pk_bf16_f32 v55, v60, v61
	v_cvt_pk_bf16_f32 v56, v56, v57
	v_cvt_pk_bf16_f32 v57, v62, v63
	global_store_dwordx4 v[66:67], v[54:57], off offset:256
	s_nop 1
	v_mov_b32_e32 v54, v3
	s_nop 1
	v_permlane16_swap_b32_e32 v3, v54
	v_add_f32_e32 v3, v3, v54
	v_mov_b32_e32 v54, v3
	s_nop 1
	v_permlane32_swap_b32_e32 v3, v54
	s_and_saveexec_b64 s[4:5], s[0:1]
	s_cbranch_execz .LBB0_455
	v_add_f32_e32 v3, v3, v54
	global_atomic_add_f32 v[134:135], v3, off offset:512
.LBB0_455:
	s_or_b64 exec, exec, s[4:5]
	v_or_b32_e32 v86, 32, v118
	v_ashrrev_i32_e32 v87, 31, v86
	v_lshlrev_b64 v[54:55], 14, v[86:87]
	v_lshl_add_u64 v[58:59], v[186:187], 0, v[54:55]
	global_load_dwordx4 v[62:65], v[58:59], off offset:16 nt
	global_load_dwordx4 v[66:69], v[58:59], off nt
	global_load_dwordx4 v[54:57], v[58:59], off offset:528 nt
	s_nop 0
	global_load_dwordx4 v[58:61], v[58:59], off offset:512 nt
	s_waitcnt vmcnt(8)
	v_pk_add_f32 v[52:53], v[52:53], v[84:85]
	v_pk_add_f32 v[50:51], v[50:51], v[82:83]
	v_pk_add_f32 v[80:81], v[48:49], v[80:81]
	v_pk_add_f32 v[48:49], v[46:47], v[78:79]
	v_mul_f32_e32 v3, v51, v51
	v_mul_f32_e32 v46, v53, v53
	v_fmac_f32_e32 v3, v50, v50
	v_fmac_f32_e32 v46, v52, v52
	v_add_f32_e32 v3, v3, v46
	v_mul_f32_e32 v46, v49, v49
	v_mul_f32_e32 v47, v81, v81
	v_fmac_f32_e32 v46, v48, v48
	v_fmac_f32_e32 v47, v80, v80
	v_lshlrev_b64 v[88:89], 13, v[102:103]
	v_add_f32_e32 v46, v46, v47
	v_add_f32_e32 v3, v46, v3
	v_cvt_pk_bf16_f32 v46, v50, v51
	v_lshl_add_u64 v[50:51], s[42:43], 0, v[88:89]
	v_cvt_pk_bf16_f32 v47, v52, v53
	v_cvt_pk_bf16_f32 v48, v48, v49
	v_cvt_pk_bf16_f32 v49, v80, v81
	v_lshl_add_u64 v[50:51], v[4:5], 1, v[50:51]
	s_waitcnt vmcnt(6)
	v_pk_add_f32 v[44:45], v[44:45], v[76:77]
	v_pk_add_f32 v[42:43], v[42:43], v[74:75]
	global_store_dwordx4 v[50:51], v[46:49], off
	s_nop 1
	v_pk_add_f32 v[46:47], v[40:41], v[72:73]
	v_pk_add_f32 v[40:41], v[38:39], v[70:71]
	v_mul_f32_e32 v38, v43, v43
	v_mul_f32_e32 v39, v45, v45
	v_fmac_f32_e32 v38, v42, v42
	v_fmac_f32_e32 v39, v44, v44
	v_add_f32_e32 v38, v38, v39
	v_mul_f32_e32 v39, v41, v41
	v_mul_f32_e32 v48, v47, v47
	v_fmac_f32_e32 v39, v40, v40
	v_fmac_f32_e32 v48, v46, v46
	v_add_f32_e32 v39, v39, v48
	v_add_f32_e32 v38, v39, v38
	v_add_f32_e32 v3, v38, v3
	v_cvt_pk_bf16_f32 v38, v42, v43
	v_cvt_pk_bf16_f32 v39, v44, v45
	v_cvt_pk_bf16_f32 v40, v40, v41
	v_cvt_pk_bf16_f32 v41, v46, v47
	global_store_dwordx4 v[50:51], v[38:41], off offset:256
	s_nop 1
	v_mov_b32_e32 v38, v3
	s_nop 1
	v_permlane16_swap_b32_e32 v3, v38
	v_add_f32_e32 v3, v3, v38
	v_mov_b32_e32 v38, v3
	s_nop 1
	v_permlane32_swap_b32_e32 v3, v38
	s_and_saveexec_b64 s[4:5], s[0:1]
	s_cbranch_execz .LBB0_457
	v_add_f32_e32 v3, v3, v38
	global_atomic_add_f32 v[134:135], v3, off offset:576
.LBB0_457:
	s_or_b64 exec, exec, s[4:5]
	v_or_b32_e32 v70, 48, v118
	v_ashrrev_i32_e32 v71, 31, v70
	v_lshlrev_b64 v[38:39], 14, v[70:71]
	v_lshl_add_u64 v[42:43], v[186:187], 0, v[38:39]
	global_load_dwordx4 v[46:49], v[42:43], off offset:16 nt
	global_load_dwordx4 v[50:53], v[42:43], off nt
	global_load_dwordx4 v[38:41], v[42:43], off offset:528 nt
	s_nop 0
	global_load_dwordx4 v[42:45], v[42:43], off offset:512 nt
	s_waitcnt vmcnt(8)
	v_pk_add_f32 v[36:37], v[36:37], v[68:69]
	v_pk_add_f32 v[34:35], v[34:35], v[66:67]
	v_pk_add_f32 v[64:65], v[32:33], v[64:65]
	v_pk_add_f32 v[32:33], v[30:31], v[62:63]
	v_mul_f32_e32 v3, v35, v35
	v_mul_f32_e32 v30, v37, v37
	v_fmac_f32_e32 v3, v34, v34
	v_fmac_f32_e32 v30, v36, v36
	v_add_f32_e32 v3, v3, v30
	v_mul_f32_e32 v30, v33, v33
	v_mul_f32_e32 v31, v65, v65
	v_fmac_f32_e32 v30, v32, v32
	v_fmac_f32_e32 v31, v64, v64
	v_lshlrev_b64 v[72:73], 13, v[86:87]
	v_add_f32_e32 v30, v30, v31
	v_add_f32_e32 v3, v30, v3
	v_cvt_pk_bf16_f32 v30, v34, v35
	v_lshl_add_u64 v[34:35], s[42:43], 0, v[72:73]
	v_cvt_pk_bf16_f32 v31, v36, v37
	v_cvt_pk_bf16_f32 v32, v32, v33
	v_cvt_pk_bf16_f32 v33, v64, v65
	v_lshl_add_u64 v[34:35], v[4:5], 1, v[34:35]
	s_waitcnt vmcnt(6)
	v_pk_add_f32 v[28:29], v[28:29], v[60:61]
	v_pk_add_f32 v[26:27], v[26:27], v[58:59]
	global_store_dwordx4 v[34:35], v[30:33], off
	s_nop 1
	v_pk_add_f32 v[30:31], v[24:25], v[56:57]
	v_pk_add_f32 v[24:25], v[22:23], v[54:55]
	v_mul_f32_e32 v22, v27, v27
	v_mul_f32_e32 v23, v29, v29
	v_fmac_f32_e32 v22, v26, v26
	v_fmac_f32_e32 v23, v28, v28
	v_add_f32_e32 v22, v22, v23
	v_mul_f32_e32 v23, v25, v25
	v_mul_f32_e32 v32, v31, v31
	v_fmac_f32_e32 v23, v24, v24
	v_fmac_f32_e32 v32, v30, v30
	v_add_f32_e32 v23, v23, v32
	v_add_f32_e32 v22, v23, v22
	v_add_f32_e32 v3, v22, v3
	v_cvt_pk_bf16_f32 v22, v26, v27
	v_cvt_pk_bf16_f32 v23, v28, v29
	v_cvt_pk_bf16_f32 v24, v24, v25
	v_cvt_pk_bf16_f32 v25, v30, v31
	global_store_dwordx4 v[34:35], v[22:25], off offset:256
	s_nop 1
	v_mov_b32_e32 v22, v3
	s_nop 1
	v_permlane16_swap_b32_e32 v3, v22
	v_add_f32_e32 v3, v3, v22
	v_mov_b32_e32 v22, v3
	s_nop 1
	v_permlane32_swap_b32_e32 v3, v22
	s_and_saveexec_b64 s[4:5], s[0:1]
	s_cbranch_execz .LBB0_459
	v_add_f32_e32 v3, v3, v22
	global_atomic_add_f32 v[134:135], v3, off offset:640

; DI float bflo(unsigned w) { return __uint_as_float(w << 16); }
; DI float bfhi(unsigned w) { return __uint_as_float(w & 0xffff0000u); }
; #define EF_LOAD(slot_, g_) do { const size_t o_ = (size_t)(row0 + ((g_) >> 2) * HALF + ((g_) & 3) * 16) * 4096 + col0; \
;             _Pragma("unroll") for (int bj = 0; bj < 2; ++bj) q16[slot_][bj] = *(const u32x4*)(base16 + o_ + bj * HALF); } while (0)
;     DI void operator()(f32x4 (&acc)[2][2][4][2], const Unit& u, int wr, int wc, int fr, int fq) const {
;     ...
;         EF_LOAD(0, 0); EF_LOAD(1, 1);
; #pragma unroll
;         for (int g = 0; g < 8; ++g) { const int ai = g >> 2, m = g & 3; const int row = row0 + ai * HALF + m * 16;
;             f32x4 cur[2][2];
; #pragma unroll
;             for (int bj = 0; bj < 2; ++bj) { const u32x4 w = q16[g & 1][bj]; cur[bj][0] = (f32x4){bflo(w.x), bfhi(w.x), bflo(w.y), bfhi(w.y)}; cur[bj][1] = (f32x4){bflo(w.z), bfhi(w.z), bflo(w.w), bfhi(w.w)}; }
;             if (g + 2 < 8) EF_LOAD(g & 1, g + 2);
;             const float s = __builtin_amdgcn_rsqf(ssq_epi[row] * (1.0f / 8192.0f) + 1e-6f);
;             float ss = 0.f;
; #pragma unroll
;             for (int bj = 0; bj < 2; ++bj) { const f32x4 v0 = cur[bj][0] + acc[ai][bj][m][0] * s, v1 = cur[bj][1] + acc[ai][bj][m][1] * s;
;                 ss += ((v0[0] * v0[0] + v0[1] * v0[1]) + (v0[2] * v0[2] + v0[3] * v0[3])) + ((v1[0] * v1[0] + v1[1] * v1[1]) + (v1[2] * v1[2] + v1[3] * v1[3]));
;                 acc[ai][bj][m][0] = v0; acc[ai][bj][m][1] = v1; }
;             ss = fq_sum(ss);
;             if (fq == 0) unsafeAtomicAdd(ssq_out + row, ss); }
.LBB0_885:
	v_lshl_add_u32 v164, s62, 8, v167
	v_lshl_or_b32 v168, s34, 8, v191
	v_ashrrev_i32_e32 v165, 31, v164
	v_ashrrev_i32_e32 v169, 31, v168
	v_lshlrev_b64 v[128:129], 13, v[164:165]
	v_lshl_add_u64 v[184:185], s[42:43], 0, v[128:129]
	v_lshlrev_b64 v[128:129], 1, v[168:169]
	v_lshl_add_u64 v[130:131], v[184:185], 0, v[128:129]
	v_lshl_add_u64 v[186:187], v[164:165], 2, s[50:51]
	global_load_dwordx4 v[170:173], v[130:131], off nt
	global_load_dwordx4 v[174:177], v[130:131], off offset:256 nt
	global_load_dword v199, v[186:187], off
	v_or_b32_e32 v162, 16, v164
	v_or_b32_e32 v160, 32, v164
	v_ashrrev_i32_e32 v163, 31, v162
	v_ashrrev_i32_e32 v161, 31, v160
	v_lshlrev_b64 v[130:131], 13, v[162:163]
	v_lshlrev_b64 v[132:133], 13, v[160:161]
	v_lshl_add_u64 v[130:131], s[42:43], 0, v[130:131]
	v_lshl_add_u64 v[132:133], s[42:43], 0, v[132:133]
	v_lshl_add_u64 v[130:131], v[130:131], 0, v[128:129]
	v_lshl_add_u64 v[128:129], v[132:133], 0, v[128:129]
	global_load_dwordx4 v[140:143], v[130:131], off nt
	global_load_dwordx4 v[136:139], v[130:131], off offset:256 nt
	global_load_dwordx4 v[132:135], v[128:129], off nt
	s_nop 0
	global_load_dwordx4 v[128:131], v[128:129], off offset:256 nt
	s_waitcnt vmcnt(0)
	v_lshlrev_b32_e32 v180, 16, v172
	v_and_b32_e32 v181, 0xffff0000, v172
	v_fmamk_f32 v172, v199, 0x39000000, v195
	v_rsq_f32_e32 v200, v172
	v_lshlrev_b32_e32 v178, 16, v170
	v_and_b32_e32 v179, 0xffff0000, v170
	v_lshlrev_b32_e32 v170, 16, v171
	v_and_b32_e32 v171, 0xffff0000, v171
	v_lshlrev_b32_e32 v182, 16, v173
	v_and_b32_e32 v183, 0xffff0000, v173
	v_lshlrev_b32_e32 v188, 16, v174
	v_and_b32_e32 v189, 0xffff0000, v174
	v_lshlrev_b32_e32 v196, 16, v175
	v_and_b32_e32 v197, 0xffff0000, v175
	v_lshlrev_b32_e32 v198, 16, v176
	v_and_b32_e32 v199, 0xffff0000, v176
	v_lshlrev_b32_e32 v202, 16, v177
	v_and_b32_e32 v203, 0xffff0000, v177
	v_pk_fma_f32 v[126:127], v[126:127], v[200:201], v[170:171] op_sel_hi:[1,0,1]
	v_pk_fma_f32 v[172:173], v[124:125], v[200:201], v[178:179] op_sel_hi:[1,0,1]
	v_pk_fma_f32 v[124:125], v[122:123], v[200:201], v[182:183] op_sel_hi:[1,0,1]
	v_pk_fma_f32 v[174:175], v[120:121], v[200:201], v[180:181] op_sel_hi:[1,0,1]
	v_pk_fma_f32 v[176:177], v[118:119], v[200:201], v[196:197] op_sel_hi:[1,0,1]
	v_pk_fma_f32 v[180:181], v[116:117], v[200:201], v[188:189] op_sel_hi:[1,0,1]
	v_pk_fma_f32 v[170:171], v[114:115], v[200:201], v[202:203] op_sel_hi:[1,0,1]
	v_pk_fma_f32 v[178:179], v[112:113], v[200:201], v[198:199] op_sel_hi:[1,0,1]
	v_mul_f32_e32 v112, v173, v173
	v_mul_f32_e32 v113, v127, v127
	v_mul_f32_e32 v114, v175, v175
	v_mul_f32_e32 v115, v125, v125
	v_mul_f32_e32 v116, v181, v181
	v_mul_f32_e32 v117, v177, v177
	v_mul_f32_e32 v118, v179, v179
	v_mul_f32_e32 v119, v171, v171
	v_fmac_f32_e32 v112, v172, v172
	v_fmac_f32_e32 v113, v126, v126
	v_fmac_f32_e32 v114, v174, v174
	v_fmac_f32_e32 v115, v124, v124
	v_fmac_f32_e32 v116, v180, v180
	v_fmac_f32_e32 v117, v176, v176
	v_fmac_f32_e32 v118, v178, v178
	v_fmac_f32_e32 v119, v170, v170
	v_add_f32_e32 v112, v112, v113
	v_add_f32_e32 v113, v114, v115
	v_add_f32_e32 v114, v116, v117
	v_add_f32_e32 v115, v118, v119
	v_add_f32_e32 v112, v112, v113
	v_add_f32_e32 v113, v114, v115
	v_add_f32_e32 v112, v112, v113
	v_mov_b32_e32 v113, v112
	s_nop 1
	v_permlane16_swap_b32_e32 v112, v113
	v_add_f32_e32 v112, v112, v113
	v_mov_b32_e32 v113, v112
	s_nop 1
	v_permlane32_swap_b32_e32 v112, v113
	v_lshl_add_u64 v[120:121], v[164:165], 2, s[12:13]
	s_and_saveexec_b64 s[6:7], s[0:1]
	s_cbranch_execz .LBB0_887
	v_add_f32_e32 v112, v112, v113
	global_atomic_add_f32 v[120:121], v112, off
.LBB0_887:
	s_or_b64 exec, exec, s[6:7]
	v_lshl_add_u64 v[112:113], v[162:163], 2, s[50:51]
	global_load_dword v201, v[112:113], off
	v_or_b32_e32 v122, 48, v164
	v_ashrrev_i32_e32 v123, 31, v122
	v_lshlrev_b64 v[112:113], 13, v[122:123]
	v_lshl_add_u64 v[112:113], s[42:43], 0, v[112:113]
	v_lshl_add_u64 v[112:113], v[168:169], 1, v[112:113]
	global_load_dwordx4 v[116:119], v[112:113], off nt
	s_nop 0
	global_load_dwordx4 v[112:115], v[112:113], off offset:256 nt
	v_lshlrev_b32_e32 v196, 16, v136
	v_and_b32_e32 v197, 0xffff0000, v136
	v_lshlrev_b32_e32 v182, 16, v140
	v_and_b32_e32 v183, 0xffff0000, v140
	v_lshlrev_b32_e32 v140, 16, v141
	v_and_b32_e32 v141, 0xffff0000, v141
	v_lshlrev_b32_e32 v188, 16, v142
	v_and_b32_e32 v189, 0xffff0000, v142
	v_lshlrev_b32_e32 v142, 16, v143
	v_and_b32_e32 v143, 0xffff0000, v143
	v_lshlrev_b32_e32 v198, 16, v137
	v_and_b32_e32 v199, 0xffff0000, v137
	v_lshlrev_b32_e32 v200, 16, v138
	s_waitcnt vmcnt(2)
	v_fmamk_f32 v136, v201, 0x39000000, v195
	v_rsq_f32_e32 v202, v136
	v_and_b32_e32 v201, 0xffff0000, v138
	v_lshlrev_b32_e32 v138, 16, v139
	v_and_b32_e32 v139, 0xffff0000, v139
	v_pk_fma_f32 v[110:111], v[110:111], v[202:203], v[140:141] op_sel_hi:[1,0,1]
	v_pk_fma_f32 v[108:109], v[108:109], v[202:203], v[182:183] op_sel_hi:[1,0,1]
	v_pk_fma_f32 v[106:107], v[106:107], v[202:203], v[142:143] op_sel_hi:[1,0,1]
	v_pk_fma_f32 v[136:137], v[104:105], v[202:203], v[188:189] op_sel_hi:[1,0,1]
	v_pk_fma_f32 v[140:141], v[102:103], v[202:203], v[198:199] op_sel_hi:[1,0,1]
	v_pk_fma_f32 v[182:183], v[100:101], v[202:203], v[196:197] op_sel_hi:[1,0,1]
	v_pk_fma_f32 v[138:139], v[98:99], v[202:203], v[138:139] op_sel_hi:[1,0,1]
	v_pk_fma_f32 v[142:143], v[96:97], v[202:203], v[200:201] op_sel_hi:[1,0,1]
	v_mul_f32_e32 v96, v109, v109
	v_mul_f32_e32 v97, v111, v111
	v_mul_f32_e32 v98, v137, v137
	v_mul_f32_e32 v99, v107, v107
	v_mul_f32_e32 v100, v183, v183
	v_mul_f32_e32 v101, v141, v141
	v_mul_f32_e32 v102, v143, v143
	v_mul_f32_e32 v103, v139, v139
	v_fmac_f32_e32 v96, v108, v108
	v_fmac_f32_e32 v97, v110, v110
	v_fmac_f32_e32 v98, v136, v136
	v_fmac_f32_e32 v99, v106, v106
	v_fmac_f32_e32 v100, v182, v182
	v_fmac_f32_e32 v101, v140, v140
	v_fmac_f32_e32 v102, v142, v142
	v_fmac_f32_e32 v103, v138, v138
	v_add_f32_e32 v96, v96, v97
	v_add_f32_e32 v97, v98, v99
	v_add_f32_e32 v98, v100, v101
	v_add_f32_e32 v99, v102, v103
	v_add_f32_e32 v96, v96, v97
	v_add_f32_e32 v97, v98, v99
	v_add_f32_e32 v96, v96, v97
	v_mov_b32_e32 v97, v96
	s_nop 1
	v_permlane16_swap_b32_e32 v96, v97
	v_add_f32_e32 v96, v96, v97
	v_mov_b32_e32 v97, v96
	s_nop 1
	v_permlane32_swap_b32_e32 v96, v97
	s_and_saveexec_b64 s[6:7], s[0:1]
	s_cbranch_execz .LBB0_889
	v_add_f32_e32 v96, v96, v97
	global_atomic_add_f32 v[120:121], v96, off offset:64
; DI float bflo(unsigned w) { return __uint_as_float(w << 16); }
; DI float bfhi(unsigned w) { return __uint_as_float(w & 0xffff0000u); }
; #define EF_LOAD(slot_, g_) do { const size_t o_ = (size_t)(row0 + ((g_) >> 2) * HALF + ((g_) & 3) * 16) * 4096 + col0; \
;             _Pragma("unroll") for (int bj = 0; bj < 2; ++bj) q16[slot_][bj] = *(const u32x4*)(base16 + o_ + bj * HALF); } while (0)
;     DI void operator()(f32x4 (&acc)[2][2][4][2], const Unit& u, int wr, int wc, int fr, int fq) const {
;     ...
;         for (int g = 0; g < 8; ++g) { const int ai = g >> 2, m = g & 3; const int row = row0 + ai * HALF + m * 16;
;             f32x4 cur[2][2];
; #pragma unroll
;             for (int bj = 0; bj < 2; ++bj) { const u32x4 w = q16[g & 1][bj]; cur[bj][0] = (f32x4){bflo(w.x), bfhi(w.x), bflo(w.y), bfhi(w.y)}; cur[bj][1] = (f32x4){bflo(w.z), bfhi(w.z), bflo(w.w), bfhi(w.w)}; }
;             if (g + 2 < 8) EF_LOAD(g & 1, g + 2);
;             const float s = __builtin_amdgcn_rsqf(ssq_epi[row] * (1.0f / 8192.0f) + 1e-6f);
;             float ss = 0.f;
; #pragma unroll
;             for (int bj = 0; bj < 2; ++bj) { const f32x4 v0 = cur[bj][0] + acc[ai][bj][m][0] * s, v1 = cur[bj][1] + acc[ai][bj][m][1] * s;
;                 ss += ((v0[0] * v0[0] + v0[1] * v0[1]) + (v0[2] * v0[2] + v0[3] * v0[3])) + ((v1[0] * v1[0] + v1[1] * v1[1]) + (v1[2] * v1[2] + v1[3] * v1[3]));
;                 acc[ai][bj][m][0] = v0; acc[ai][bj][m][1] = v1; }
;             ss = fq_sum(ss);
;             if (fq == 0) unsafeAtomicAdd(ssq_out + row, ss); }
.LBB0_889:
	s_or_b64 exec, exec, s[6:7]
	v_lshl_add_u64 v[96:97], v[160:161], 2, s[50:51]
	global_load_dword v201, v[96:97], off
	v_add_u32_e32 v104, 0x80, v164
	v_ashrrev_i32_e32 v105, 31, v104
	v_lshlrev_b64 v[96:97], 13, v[104:105]
	v_lshl_add_u64 v[96:97], s[42:43], 0, v[96:97]
	v_lshl_add_u64 v[96:97], v[168:169], 1, v[96:97]
	global_load_dwordx4 v[100:103], v[96:97], off nt
	s_nop 0
	global_load_dwordx4 v[96:99], v[96:97], off offset:256 nt
	v_lshlrev_b32_e32 v188, 16, v132
	v_and_b32_e32 v189, 0xffff0000, v132
	v_lshlrev_b32_e32 v132, 16, v133
	v_and_b32_e32 v133, 0xffff0000, v133
	v_lshlrev_b32_e32 v196, 16, v134
	v_and_b32_e32 v197, 0xffff0000, v134
	v_lshlrev_b32_e32 v134, 16, v135
	v_and_b32_e32 v135, 0xffff0000, v135
	v_lshlrev_b32_e32 v198, 16, v128
	v_and_b32_e32 v199, 0xffff0000, v128
	v_lshlrev_b32_e32 v128, 16, v129
	v_and_b32_e32 v129, 0xffff0000, v129
	v_lshlrev_b32_e32 v200, 16, v130
	v_lshlrev_b32_e32 v204, 16, v131
	v_and_b32_e32 v205, 0xffff0000, v131
	s_waitcnt vmcnt(2)
	v_fmamk_f32 v201, v201, 0x39000000, v195
	v_rsq_f32_e32 v202, v201
	v_and_b32_e32 v201, 0xffff0000, v130
	v_pk_fma_f32 v[94:95], v[94:95], v[202:203], v[132:133] op_sel_hi:[1,0,1]
	v_pk_fma_f32 v[92:93], v[92:93], v[202:203], v[188:189] op_sel_hi:[1,0,1]
	v_pk_fma_f32 v[90:91], v[90:91], v[202:203], v[134:135] op_sel_hi:[1,0,1]
	v_pk_fma_f32 v[88:89], v[88:89], v[202:203], v[196:197] op_sel_hi:[1,0,1]
	v_pk_fma_f32 v[130:131], v[86:87], v[202:203], v[128:129] op_sel_hi:[1,0,1]
	v_pk_fma_f32 v[134:135], v[84:85], v[202:203], v[198:199] op_sel_hi:[1,0,1]
	v_pk_fma_f32 v[128:129], v[82:83], v[202:203], v[204:205] op_sel_hi:[1,0,1]
	v_pk_fma_f32 v[132:133], v[80:81], v[202:203], v[200:201] op_sel_hi:[1,0,1]
	v_mul_f32_e32 v80, v93, v93
	v_mul_f32_e32 v81, v95, v95
	v_mul_f32_e32 v82, v89, v89
	v_mul_f32_e32 v83, v91, v91
	v_mul_f32_e32 v84, v135, v135
	v_mul_f32_e32 v85, v131, v131
	v_mul_f32_e32 v86, v133, v133
	v_mul_f32_e32 v87, v129, v129
	v_fmac_f32_e32 v80, v92, v92
	v_fmac_f32_e32 v81, v94, v94
	v_fmac_f32_e32 v82, v88, v88
	v_fmac_f32_e32 v83, v90, v90
	v_fmac_f32_e32 v84, v134, v134
	v_fmac_f32_e32 v85, v130, v130
	v_fmac_f32_e32 v86, v132, v132
	v_fmac_f32_e32 v87, v128, v128
	v_add_f32_e32 v80, v80, v81
	v_add_f32_e32 v81, v82, v83
	v_add_f32_e32 v82, v84, v85
	v_add_f32_e32 v83, v86, v87
	v_add_f32_e32 v80, v80, v81
	v_add_f32_e32 v81, v82, v83
	v_add_f32_e32 v80, v80, v81
	v_mov_b32_e32 v81, v80
	s_nop 1
	v_permlane16_swap_b32_e32 v80, v81
	v_add_f32_e32 v80, v80, v81
	v_mov_b32_e32 v81, v80
	s_nop 1
	v_permlane32_swap_b32_e32 v80, v81
	s_and_saveexec_b64 s[6:7], s[0:1]
	s_cbranch_execz .LBB0_891
	v_add_f32_e32 v80, v80, v81
	global_atomic_add_f32 v[120:121], v80, off offset:128
.LBB0_891:
	s_or_b64 exec, exec, s[6:7]
	v_lshl_add_u64 v[80:81], v[122:123], 2, s[50:51]
	global_load_dword v201, v[80:81], off
	v_lshl_add_u64 v[80:81], v[168:169], 1, v[184:185]
	v_lshl_add_u64 v[82:83], v[80:81], 0, s[24:25]
	v_add_co_u32_e32 v80, vcc, s60, v80
	v_lshlrev_b32_e32 v196, 16, v112
	s_nop 0
	v_addc_co_u32_e32 v81, vcc, 0, v81, vcc
	global_load_dwordx4 v[84:87], v[80:81], off nt
	s_nop 0
	global_load_dwordx4 v[80:83], v[82:83], off offset:256 nt
	v_and_b32_e32 v197, 0xffff0000, v112
	v_lshlrev_b32_e32 v184, 16, v116
	v_and_b32_e32 v185, 0xffff0000, v116
	v_lshlrev_b32_e32 v116, 16, v117
	v_and_b32_e32 v117, 0xffff0000, v117
	v_lshlrev_b32_e32 v188, 16, v118
	v_and_b32_e32 v189, 0xffff0000, v118
	v_lshlrev_b32_e32 v118, 16, v119
	v_and_b32_e32 v119, 0xffff0000, v119
	v_lshlrev_b32_e32 v198, 16, v113
	v_and_b32_e32 v199, 0xffff0000, v113
	v_lshlrev_b32_e32 v200, 16, v114
	s_waitcnt vmcnt(2)
	v_fmamk_f32 v112, v201, 0x39000000, v195
	v_rsq_f32_e32 v202, v112
	v_and_b32_e32 v201, 0xffff0000, v114
	v_lshlrev_b32_e32 v114, 16, v115
	v_and_b32_e32 v115, 0xffff0000, v115
	v_pk_fma_f32 v[78:79], v[78:79], v[202:203], v[116:117] op_sel_hi:[1,0,1]
	v_pk_fma_f32 v[76:77], v[76:77], v[202:203], v[184:185] op_sel_hi:[1,0,1]
	v_pk_fma_f32 v[74:75], v[74:75], v[202:203], v[118:119] op_sel_hi:[1,0,1]
	v_pk_fma_f32 v[112:113], v[72:73], v[202:203], v[188:189] op_sel_hi:[1,0,1]
	v_pk_fma_f32 v[116:117], v[70:71], v[202:203], v[198:199] op_sel_hi:[1,0,1]
	v_pk_fma_f32 v[184:185], v[68:69], v[202:203], v[196:197] op_sel_hi:[1,0,1]
	v_pk_fma_f32 v[114:115], v[66:67], v[202:203], v[114:115] op_sel_hi:[1,0,1]
	v_pk_fma_f32 v[118:119], v[64:65], v[202:203], v[200:201] op_sel_hi:[1,0,1]
	v_mul_f32_e32 v64, v77, v77
	v_mul_f32_e32 v65, v79, v79
	v_mul_f32_e32 v66, v113, v113
	v_mul_f32_e32 v67, v75, v75
	v_mul_f32_e32 v68, v185, v185
	v_mul_f32_e32 v69, v117, v117
	v_mul_f32_e32 v70, v119, v119
	v_mul_f32_e32 v71, v115, v115
	v_fmac_f32_e32 v64, v76, v76
	v_fmac_f32_e32 v65, v78, v78
	v_fmac_f32_e32 v66, v112, v112
	v_fmac_f32_e32 v67, v74, v74
	v_fmac_f32_e32 v68, v184, v184
	v_fmac_f32_e32 v69, v116, v116
	v_fmac_f32_e32 v70, v118, v118
	v_fmac_f32_e32 v71, v114, v114
	v_add_f32_e32 v64, v64, v65
	v_add_f32_e32 v65, v66, v67
	v_add_f32_e32 v66, v68, v69
	v_add_f32_e32 v67, v70, v71
	v_add_f32_e32 v64, v64, v65
	v_add_f32_e32 v65, v66, v67
	v_add_f32_e32 v64, v64, v65
	v_mov_b32_e32 v65, v64
	s_nop 1
	v_permlane16_swap_b32_e32 v64, v65
	v_add_f32_e32 v64, v64, v65
	v_mov_b32_e32 v65, v64
	s_nop 1
	v_permlane32_swap_b32_e32 v64, v65
	s_and_saveexec_b64 s[6:7], s[0:1]
	s_cbranch_execz .LBB0_893
	v_add_f32_e32 v64, v64, v65
	global_atomic_add_f32 v[120:121], v64, off offset:192
; DI float bflo(unsigned w) { return __uint_as_float(w << 16); }
; DI float bfhi(unsigned w) { return __uint_as_float(w & 0xffff0000u); }
; #define EF_LOAD(slot_, g_) do { const size_t o_ = (size_t)(row0 + ((g_) >> 2) * HALF + ((g_) & 3) * 16) * 4096 + col0; \
;             _Pragma("unroll") for (int bj = 0; bj < 2; ++bj) q16[slot_][bj] = *(const u32x4*)(base16 + o_ + bj * HALF); } while (0)
;     DI void operator()(f32x4 (&acc)[2][2][4][2], const Unit& u, int wr, int wc, int fr, int fq) const {
;     ...
;         for (int g = 0; g < 8; ++g) { const int ai = g >> 2, m = g & 3; const int row = row0 + ai * HALF + m * 16;
;             f32x4 cur[2][2];
; #pragma unroll
;             for (int bj = 0; bj < 2; ++bj) { const u32x4 w = q16[g & 1][bj]; cur[bj][0] = (f32x4){bflo(w.x), bfhi(w.x), bflo(w.y), bfhi(w.y)}; cur[bj][1] = (f32x4){bflo(w.z), bfhi(w.z), bflo(w.w), bfhi(w.w)}; }
;             if (g + 2 < 8) EF_LOAD(g & 1, g + 2);
;             const float s = __builtin_amdgcn_rsqf(ssq_epi[row] * (1.0f / 8192.0f) + 1e-6f);
;             float ss = 0.f;
; #pragma unroll
;             for (int bj = 0; bj < 2; ++bj) { const f32x4 v0 = cur[bj][0] + acc[ai][bj][m][0] * s, v1 = cur[bj][1] + acc[ai][bj][m][1] * s;
;                 ss += ((v0[0] * v0[0] + v0[1] * v0[1]) + (v0[2] * v0[2] + v0[3] * v0[3])) + ((v1[0] * v1[0] + v1[1] * v1[1]) + (v1[2] * v1[2] + v1[3] * v1[3]));
;                 acc[ai][bj][m][0] = v0; acc[ai][bj][m][1] = v1; }
;             ss = fq_sum(ss);
;             if (fq == 0) unsafeAtomicAdd(ssq_out + row, ss); }
.LBB0_893:
	s_or_b64 exec, exec, s[6:7]
	global_load_dword v201, v[186:187], off offset:512
	v_or_b32_e32 v72, 32, v104
	v_ashrrev_i32_e32 v73, 31, v72
	v_lshlrev_b64 v[64:65], 13, v[72:73]
	v_lshl_add_u64 v[64:65], s[42:43], 0, v[64:65]
	v_lshl_add_u64 v[64:65], v[168:169], 1, v[64:65]
	global_load_dwordx4 v[68:71], v[64:65], off nt
	s_nop 0
	global_load_dwordx4 v[64:67], v[64:65], off offset:256 nt
	v_lshlrev_b32_e32 v196, 16, v96
	v_and_b32_e32 v197, 0xffff0000, v96
	v_lshlrev_b32_e32 v186, 16, v100
	v_and_b32_e32 v187, 0xffff0000, v100
	v_lshlrev_b32_e32 v100, 16, v101
	v_and_b32_e32 v101, 0xffff0000, v101
	v_lshlrev_b32_e32 v188, 16, v102
	v_and_b32_e32 v189, 0xffff0000, v102
	v_lshlrev_b32_e32 v102, 16, v103
	v_and_b32_e32 v103, 0xffff0000, v103
	v_lshlrev_b32_e32 v198, 16, v97
	v_and_b32_e32 v199, 0xffff0000, v97
	v_lshlrev_b32_e32 v200, 16, v98
	s_waitcnt vmcnt(2)
	v_fmamk_f32 v96, v201, 0x39000000, v195
	v_rsq_f32_e32 v202, v96
	v_and_b32_e32 v201, 0xffff0000, v98
	v_lshlrev_b32_e32 v98, 16, v99
	v_and_b32_e32 v99, 0xffff0000, v99
	v_pk_fma_f32 v[62:63], v[62:63], v[202:203], v[100:101] op_sel_hi:[1,0,1]
	v_pk_fma_f32 v[60:61], v[60:61], v[202:203], v[186:187] op_sel_hi:[1,0,1]
	v_pk_fma_f32 v[58:59], v[58:59], v[202:203], v[102:103] op_sel_hi:[1,0,1]
	v_pk_fma_f32 v[96:97], v[56:57], v[202:203], v[188:189] op_sel_hi:[1,0,1]
	v_pk_fma_f32 v[100:101], v[54:55], v[202:203], v[198:199] op_sel_hi:[1,0,1]
	v_pk_fma_f32 v[186:187], v[52:53], v[202:203], v[196:197] op_sel_hi:[1,0,1]
	v_pk_fma_f32 v[98:99], v[50:51], v[202:203], v[98:99] op_sel_hi:[1,0,1]
	v_pk_fma_f32 v[102:103], v[48:49], v[202:203], v[200:201] op_sel_hi:[1,0,1]
	v_mul_f32_e32 v48, v61, v61
	v_mul_f32_e32 v49, v63, v63
	v_mul_f32_e32 v50, v97, v97
	v_mul_f32_e32 v51, v59, v59
	v_mul_f32_e32 v52, v187, v187
	v_mul_f32_e32 v53, v101, v101
	v_mul_f32_e32 v54, v103, v103
	v_mul_f32_e32 v55, v99, v99
	v_fmac_f32_e32 v48, v60, v60
	v_fmac_f32_e32 v49, v62, v62
	v_fmac_f32_e32 v50, v96, v96
	v_fmac_f32_e32 v51, v58, v58
	v_fmac_f32_e32 v52, v186, v186
	v_fmac_f32_e32 v53, v100, v100
	v_fmac_f32_e32 v54, v102, v102
	v_fmac_f32_e32 v55, v98, v98
	v_add_f32_e32 v48, v48, v49
	v_add_f32_e32 v49, v50, v51
	v_add_f32_e32 v50, v52, v53
	v_add_f32_e32 v51, v54, v55
	v_add_f32_e32 v48, v48, v49
	v_add_f32_e32 v49, v50, v51
	v_add_f32_e32 v48, v48, v49
	v_mov_b32_e32 v49, v48
	s_nop 1
	v_permlane16_swap_b32_e32 v48, v49
	v_add_f32_e32 v48, v48, v49
	v_mov_b32_e32 v49, v48
	s_nop 1
	v_permlane32_swap_b32_e32 v48, v49
	s_and_saveexec_b64 s[6:7], s[0:1]
	s_cbranch_execz .LBB0_895
	v_add_f32_e32 v48, v48, v49
	global_atomic_add_f32 v[120:121], v48, off offset:512
.LBB0_895:
	s_or_b64 exec, exec, s[6:7]
	v_or_b32_e32 v188, 16, v104
	v_ashrrev_i32_e32 v189, 31, v188
	v_lshl_add_u64 v[48:49], v[188:189], 2, s[50:51]
	global_load_dword v203, v[48:49], off
	v_or_b32_e32 v56, 48, v104
	v_ashrrev_i32_e32 v57, 31, v56
	v_lshlrev_b64 v[48:49], 13, v[56:57]
	v_lshl_add_u64 v[48:49], s[42:43], 0, v[48:49]
	v_lshl_add_u64 v[48:49], v[168:169], 1, v[48:49]
	global_load_dwordx4 v[52:55], v[48:49], off nt
	s_nop 0
	global_load_dwordx4 v[48:51], v[48:49], off offset:256 nt
	v_lshlrev_b32_e32 v196, 16, v84
	v_and_b32_e32 v197, 0xffff0000, v84
	v_lshlrev_b32_e32 v84, 16, v85
	v_and_b32_e32 v85, 0xffff0000, v85
	v_lshlrev_b32_e32 v198, 16, v86
	v_and_b32_e32 v199, 0xffff0000, v86
	v_lshlrev_b32_e32 v86, 16, v87
	v_and_b32_e32 v87, 0xffff0000, v87
	v_lshlrev_b32_e32 v200, 16, v80
	v_and_b32_e32 v201, 0xffff0000, v80
	v_lshlrev_b32_e32 v80, 16, v81
	v_and_b32_e32 v81, 0xffff0000, v81
	v_lshlrev_b32_e32 v202, 16, v82
	s_waitcnt vmcnt(2)
	v_fmamk_f32 v203, v203, 0x39000000, v195
	v_rsq_f32_e32 v204, v203
	v_and_b32_e32 v203, 0xffff0000, v82
	v_lshlrev_b32_e32 v82, 16, v83
	v_and_b32_e32 v83, 0xffff0000, v83
	v_pk_fma_f32 v[46:47], v[46:47], v[204:205], v[84:85] op_sel_hi:[1,0,1]
	v_pk_fma_f32 v[44:45], v[44:45], v[204:205], v[196:197] op_sel_hi:[1,0,1]
	v_pk_fma_f32 v[42:43], v[42:43], v[204:205], v[86:87] op_sel_hi:[1,0,1]
	v_pk_fma_f32 v[40:41], v[40:41], v[204:205], v[198:199] op_sel_hi:[1,0,1]
	v_pk_fma_f32 v[38:39], v[38:39], v[204:205], v[80:81] op_sel_hi:[1,0,1]
	v_pk_fma_f32 v[36:37], v[36:37], v[204:205], v[200:201] op_sel_hi:[1,0,1]
	v_pk_fma_f32 v[34:35], v[34:35], v[204:205], v[82:83] op_sel_hi:[1,0,1]
	v_pk_fma_f32 v[32:33], v[32:33], v[204:205], v[202:203] op_sel_hi:[1,0,1]
	v_mul_f32_e32 v80, v45, v45
	v_mul_f32_e32 v81, v47, v47
	v_mul_f32_e32 v82, v41, v41
	v_mul_f32_e32 v83, v43, v43
	v_mul_f32_e32 v84, v37, v37
	v_mul_f32_e32 v85, v39, v39
	v_mul_f32_e32 v86, v33, v33
	v_mul_f32_e32 v87, v35, v35
	v_fmac_f32_e32 v80, v44, v44
	v_fmac_f32_e32 v81, v46, v46
	v_fmac_f32_e32 v82, v40, v40
	v_fmac_f32_e32 v83, v42, v42
	v_fmac_f32_e32 v84, v36, v36
	v_fmac_f32_e32 v85, v38, v38
	v_fmac_f32_e32 v86, v32, v32
	v_fmac_f32_e32 v87, v34, v34
	v_add_f32_e32 v80, v80, v81
	v_add_f32_e32 v81, v82, v83
	v_add_f32_e32 v82, v84, v85
	v_add_f32_e32 v83, v86, v87
	v_add_f32_e32 v80, v80, v81
	v_add_f32_e32 v81, v82, v83
	v_add_f32_e32 v80, v80, v81
	v_mov_b32_e32 v81, v80
	s_nop 1
	v_permlane16_swap_b32_e32 v80, v81
	v_add_f32_e32 v80, v80, v81
	v_mov_b32_e32 v81, v80
	s_nop 1
	v_permlane32_swap_b32_e32 v80, v81
	s_and_saveexec_b64 s[6:7], s[0:1]
	s_cbranch_execz .LBB0_897
	v_add_f32_e32 v80, v80, v81
	global_atomic_add_f32 v[120:121], v80, off offset:576
